# v28 + P3: nt on the read-once V and BZ stage loads (QA/KA/U stay default policy)
# speedup vs baseline: 1.0129x; 1.0011x over previous
.Lev_skip_a:
	s_add_i32 s34, s49, 3
	v_sub_u32_e64 v32, 60, s44 clamp
	s_and_b64 s[20:21], exec, s[38:39]
	v_readfirstlane_b32 s20, v32
	s_cselect_b32 s66, s34, s20
	s_lshl_b32 s34, s66, 13
	s_lshl_b32 s67, s66, 14
	s_add_u32 s20, s43, s67
	s_addc_u32 s21, s63, 0
	v_lshl_add_u64 v[36:37], s[20:21], 0, v[120:121]
	global_load_dwordx4 v[32:35], v120, s[20:21]
	v_add_co_u32_e64 v36, s[20:21], s60, v36
	v_lshl_add_u64 v[48:49], v[146:147], 0, s[34:35]
	s_nop 0
	v_addc_co_u32_e64 v37, s[20:21], 0, v37, s[20:21]
	s_add_u32 s20, s64, s67
	s_addc_u32 s21, s65, 0
	v_lshl_add_u64 v[44:45], s[20:21], 0, v[120:121]
	global_load_dwordx4 v[36:39], v[36:37], off
	s_lshl_b32 s34, s66, 10
	global_load_dwordx4 v[40:43], v120, s[20:21]
	v_add_co_u32_e64 v44, s[20:21], s60, v44
	v_lshl_add_u64 v[52:53], v[148:149], 0, s[34:35]
	s_nop 0
	v_addc_co_u32_e64 v45, s[20:21], 0, v45, s[20:21]
	s_lshl_b32 s20, s49, 1
	s_add_i32 s34, s20, 4
	s_waitcnt vmcnt(15)
	v_mov_b32_e32 v214, v64
	v_mov_b32_e32 v215, v65
	v_mov_b32_e32 v216, v66
	v_mov_b32_e32 v217, v67
	v_lshl_add_u64 v[64:65], v[144:145], 0, s[34:35]
	s_add_i32 s34, 0, 0x1e400
	v_mov_b32_e32 v198, v56
	v_mov_b32_e32 v199, v57
	v_mov_b32_e32 v200, v58
	v_mov_b32_e32 v201, v59
	v_mov_b32_e32 v202, v60
	v_mov_b32_e32 v203, v61
	v_mov_b32_e32 v204, v62
	v_mov_b32_e32 v205, v63
	s_waitcnt vmcnt(14)
	v_mov_b32_e32 v242, v68
	v_mov_b32_e32 v243, v69
	v_mov_b32_e32 v244, v70
	v_mov_b32_e32 v245, v71
	v_add_u32_e32 v116, s34, v143
	ds_read_b128 v[190:193], v116
	v_and_b32_e32 v66, 0xfff, v64
	v_cmp_ne_u32_e64 s[20:21], 0, v66
	v_add_u32_e32 v185, 0, v143
	v_add_u32_e32 v116, 0x1e600, v185
	s_waitcnt lgkmcnt(0)
	v_pk_mul_f32 v[192:193], v[98:99], v[192:193]
	v_pk_mul_f32 v[190:191], v[96:97], v[190:191]
	v_pk_mul_f32 v[98:99], v[102:103], v[192:193]
	v_pk_mul_f32 v[96:97], v[100:101], v[190:191]
	v_cndmask_b32_e64 v56, 0, 1, s[20:21]
	v_cvt_pk_bf16_f32 v100, v96, v97
	v_cvt_pk_bf16_f32 v101, v98, v99
	v_sub_co_u32_e64 v56, s[20:21], v64, v56
	ds_read_b128 v[116:119], v116
	ds_write_b64 v182, v[100:101]
	v_pk_mul_f32 v[100:101], v[104:105], v[190:191]
	v_pk_mul_f32 v[102:103], v[106:107], v[192:193]
	v_subbrev_co_u32_e64 v57, s[20:21], 0, v65, s[20:21]
	v_cvt_pk_bf16_f32 v104, v100, v101
	v_cvt_pk_bf16_f32 v105, v102, v103
	v_cmp_ne_u32_e64 s[20:21], s62, v66
	ds_write_b64 v182, v[104:105] offset:4352
	v_pk_mul_f32 v[104:105], v[108:109], v[190:191]
	v_pk_mul_f32 v[106:107], v[110:111], v[192:193]
	v_cndmask_b32_e64 v66, 0, 1, s[20:21]
	v_mov_b32_e32 v67, s35
	v_cvt_pk_bf16_f32 v108, v104, v105
	v_cvt_pk_bf16_f32 v109, v106, v107
	v_lshlrev_b64 v[68:69], 11, v[64:65]
	v_lshl_add_u64 v[64:65], v[64:65], 0, v[66:67]
	ds_write_b64 v182, v[108:109] offset:8704
	v_pk_mul_f32 v[108:109], v[112:113], v[190:191]
	v_pk_mul_f32 v[110:111], v[114:115], v[192:193]
	v_lshlrev_b64 v[56:57], 11, v[56:57]
	v_lshlrev_b64 v[64:65], 11, v[64:65]
	v_cvt_pk_bf16_f32 v112, v108, v109
	v_cvt_pk_bf16_f32 v113, v110, v111
	v_lshl_add_u64 v[56:57], v[134:135], 0, v[56:57]
	v_lshl_add_u64 v[60:61], v[134:135], 0, v[68:69]
	v_lshl_add_u64 v[64:65], v[134:135], 0, v[64:65]
	v_lshl_add_u64 v[68:69], v[136:137], 0, v[68:69]
	ds_write_b64 v182, v[112:113] offset:13056
	global_load_dwordx4 v[44:47], v[44:45], off
	global_load_dwordx4 v[48:51], v[48:49], off nt
	global_load_dwordx4 v[52:55], v[52:53], off
	global_load_dwordx4 v[56:59], v[56:57], off
	s_lshl_b32 s48, s48, 6
	global_load_dwordx4 v[60:63], v[60:61], off
	s_nop 0
	global_load_dwordx4 v[64:67], v[64:65], off
	s_nop 0
	global_load_dwordx4 v[68:71], v[68:69], off nt
	s_waitcnt lgkmcnt(0)
	s_barrier
	ds_read_b128 v[218:221], v170 offset:61440
	ds_read_b128 v[222:225], v171 offset:44032
	ds_read_b128 v[226:229], v172 offset:44032
	ds_read_b128 v[230:233], v170 offset:61504
	ds_read_b128 v[234:237], v171 offset:44096
	ds_read_b128 v[238:241], v172 offset:44096
	v_and_b32_e32 v250, 0xfff, v184
	v_cmp_ne_u32_e64 s[20:21], 0, v250
	v_add_u32_e32 v184, 4, v184
	s_nop 0
	v_cndmask_b32_e64 v198, 0, v198, s[20:21]
	v_cndmask_b32_e64 v199, 0, v199, s[20:21]
	v_cndmask_b32_e64 v200, 0, v200, s[20:21]
	v_cndmask_b32_e64 v201, 0, v201, s[20:21]
	v_cmp_ne_u32_e64 s[20:21], s62, v250
	v_lshlrev_b32_e32 v246, 16, v202
	v_and_b32_e32 v247, 0xffff0000, v202
	v_cndmask_b32_e64 v214, 0, v214, s[20:21]
	v_cndmask_b32_e64 v215, 0, v215, s[20:21]
	v_cndmask_b32_e64 v216, 0, v216, s[20:21]
	v_cndmask_b32_e64 v217, 0, v217, s[20:21]
	v_pk_mul_f32 v[246:247], v[8:9], v[246:247]
	v_lshlrev_b32_e32 v248, 16, v198
	v_and_b32_e32 v249, 0xffff0000, v198
	v_pk_fma_f32 v[246:247], v[0:1], v[248:249], v[246:247]
	v_lshlrev_b32_e32 v248, 16, v214
	v_and_b32_e32 v249, 0xffff0000, v214
	v_pk_fma_f32 v[246:247], v[16:17], v[248:249], v[246:247]
	v_pk_add_f32 v[246:247], v[24:25], v[246:247]
	v_lshlrev_b32_e32 v248, 16, v242
	v_and_b32_e32 v249, 0xffff0000, v242
	v_pk_mul_f32 v[246:247], v[246:247], v[248:249]
	v_cvt_pk_bf16_f32 v198, v246, v247
	v_lshlrev_b32_e32 v246, 16, v203
	v_and_b32_e32 v247, 0xffff0000, v203
	v_pk_mul_f32 v[246:247], v[10:11], v[246:247]
	v_lshlrev_b32_e32 v248, 16, v199
	v_and_b32_e32 v249, 0xffff0000, v199
	v_pk_fma_f32 v[246:247], v[2:3], v[248:249], v[246:247]
	v_lshlrev_b32_e32 v248, 16, v215
	v_and_b32_e32 v249, 0xffff0000, v215
	v_pk_fma_f32 v[246:247], v[18:19], v[248:249], v[246:247]
	v_pk_add_f32 v[246:247], v[26:27], v[246:247]
	v_lshlrev_b32_e32 v248, 16, v243
	v_and_b32_e32 v249, 0xffff0000, v243
	v_pk_mul_f32 v[246:247], v[246:247], v[248:249]
	v_cvt_pk_bf16_f32 v199, v246, v247
	v_lshlrev_b32_e32 v246, 16, v204
	v_and_b32_e32 v247, 0xffff0000, v204
	v_pk_mul_f32 v[246:247], v[12:13], v[246:247]
	v_lshlrev_b32_e32 v248, 16, v200
	v_and_b32_e32 v249, 0xffff0000, v200
	v_pk_fma_f32 v[246:247], v[4:5], v[248:249], v[246:247]
	v_lshlrev_b32_e32 v248, 16, v216
	v_and_b32_e32 v249, 0xffff0000, v216
	v_pk_fma_f32 v[246:247], v[20:21], v[248:249], v[246:247]
	v_pk_add_f32 v[246:247], v[28:29], v[246:247]
	v_lshlrev_b32_e32 v248, 16, v244
	v_and_b32_e32 v249, 0xffff0000, v244
	v_pk_mul_f32 v[246:247], v[246:247], v[248:249]
	v_cvt_pk_bf16_f32 v200, v246, v247
	v_lshlrev_b32_e32 v246, 16, v205
	v_and_b32_e32 v247, 0xffff0000, v205
	v_pk_mul_f32 v[246:247], v[14:15], v[246:247]
	v_lshlrev_b32_e32 v248, 16, v201
	v_and_b32_e32 v249, 0xffff0000, v201
	v_pk_fma_f32 v[246:247], v[6:7], v[248:249], v[246:247]
	v_lshlrev_b32_e32 v248, 16, v217
	v_and_b32_e32 v249, 0xffff0000, v217
	v_pk_fma_f32 v[246:247], v[22:23], v[248:249], v[246:247]
	v_pk_add_f32 v[246:247], v[30:31], v[246:247]
	v_lshlrev_b32_e32 v248, 16, v245
	v_and_b32_e32 v249, 0xffff0000, v245
	v_pk_mul_f32 v[246:247], v[246:247], v[248:249]
	v_cvt_pk_bf16_f32 v201, v246, v247
	global_store_dwordx4 v[152:153], v[198:201], off
	ds_read_b128 v[242:245], v170 offset:61568
	ds_read_b128 v[246:249], v171 offset:44160
	ds_read_b128 v[250:253], v172 offset:44160
	s_waitcnt lgkmcnt(6)
	v_mfma_f32_16x16x32_bf16 v[190:193], v[218:221], v[222:225], 0
	v_mfma_f32_16x16x32_bf16 v[194:197], v[218:221], v[226:229], 0
	ds_read_b128 v[218:221], v170 offset:61632
	ds_read_b128 v[222:225], v171 offset:44224
	ds_read_b128 v[226:229], v172 offset:44224
	s_waitcnt lgkmcnt(6)
	v_mfma_f32_16x16x32_bf16 v[190:193], v[230:233], v[234:237], v[190:193]
	v_mfma_f32_16x16x32_bf16 v[194:197], v[230:233], v[238:241], v[194:197]
	ds_read_b64_tr_b16 v[230:231], v206 offset:34816
	ds_read_b64_tr_b16 v[232:233], v206 offset:35392
	ds_read_b128 v[234:237], v208
	ds_read_b128 v[238:241], v209
	s_waitcnt lgkmcnt(7)
	v_mfma_f32_16x16x32_bf16 v[190:193], v[242:245], v[246:249], v[190:193]
	v_mfma_f32_16x16x32_bf16 v[194:197], v[242:245], v[250:253], v[194:197]
	ds_read_b64_tr_b16 v[242:243], v206 offset:39424
	ds_read_b64_tr_b16 v[244:245], v206 offset:40000
	ds_read_b128 v[246:249], v208 offset:64
	ds_read_b128 v[250:253], v209 offset:64
	s_waitcnt lgkmcnt(8)
	v_mfma_f32_16x16x32_bf16 v[190:193], v[218:221], v[222:225], v[190:193]
	v_mfma_f32_16x16x32_bf16 v[194:197], v[218:221], v[226:229], v[194:197]
	ds_read_b128 v[218:221], v183
	ds_read_b128 v[222:225], v171
	ds_read_b128 v[226:229], v172
	s_waitcnt lgkmcnt(7)
	v_mfma_f32_16x16x32_bf16 v[198:201], v[230:233], v[234:237], 0
	v_mfma_f32_16x16x32_bf16 v[202:205], v[230:233], v[238:241], 0
	ds_read_b128 v[230:233], v183 offset:64
	ds_read_b128 v[234:237], v171 offset:64
	ds_read_b128 v[238:241], v172 offset:64
	s_waitcnt lgkmcnt(6)
	v_mfma_f32_16x16x32_bf16 v[198:201], v[242:245], v[246:249], v[198:201]
	v_mfma_f32_16x16x32_bf16 v[202:205], v[242:245], v[250:253], v[202:205]
	ds_read_b128 v[242:245], v183 offset:128
	ds_read_b128 v[246:249], v171 offset:128
	ds_read_b128 v[250:253], v172 offset:128
	v_cndmask_b32_e32 v190, 0, v190, vcc
	v_cndmask_b32_e64 v191, 0, v191, s[6:7]
	v_cndmask_b32_e64 v192, 0, v192, s[8:9]
	v_cndmask_b32_e64 v193, 0, v193, s[10:11]
	v_cvt_pk_bf16_f32 v190, v190, v191
	v_cvt_pk_bf16_f32 v191, v192, v193
	v_cndmask_b32_e64 v194, 0, v194, s[12:13]
	v_cndmask_b32_e64 v195, 0, v195, s[14:15]
	v_cndmask_b32_e64 v196, 0, v196, s[16:17]
	v_cndmask_b32_e64 v197, 0, v197, s[18:19]
	v_cvt_pk_bf16_f32 v194, v194, v195
	v_cvt_pk_bf16_f32 v195, v196, v197
	ds_write_b64 v212, v[190:191]
	ds_write_b64 v213, v[194:195]
	s_waitcnt lgkmcnt(8)
	v_mfma_f32_16x16x32_bf16 v[198:201], v[218:221], v[222:225], v[198:201]
	v_mfma_f32_16x16x32_bf16 v[202:205], v[218:221], v[226:229], v[202:205]
	ds_read_b64_tr_b16 v[190:191], v178 offset:17408
	ds_read_b64_tr_b16 v[192:193], v178 offset:18496
	ds_read_b64_tr_b16 v[194:195], v178 offset:26112
	ds_read_b64_tr_b16 v[196:197], v178 offset:27200
	s_waitcnt lgkmcnt(9)
	v_mfma_f32_16x16x32_bf16 v[198:201], v[230:233], v[234:237], v[198:201]
	v_mfma_f32_16x16x32_bf16 v[202:205], v[230:233], v[238:241], v[202:205]
	ds_read_b128 v[230:233], v183 offset:192
	ds_read_b128 v[234:237], v171 offset:192
	ds_read_b128 v[238:241], v172 offset:192
	s_waitcnt lgkmcnt(9)
	v_mfma_f32_16x16x32_bf16 v[198:201], v[242:245], v[246:249], v[198:201]
	v_mfma_f32_16x16x32_bf16 v[202:205], v[242:245], v[250:253], v[202:205]
	ds_read_b64_tr_b16 v[242:243], v161 offset:34816
	ds_read_b64_tr_b16 v[244:245], v161 offset:35392
	ds_read_b64_tr_b16 v[246:247], v161 offset:34848
	ds_read_b64_tr_b16 v[248:249], v161 offset:35424
	s_waitcnt lgkmcnt(7)
	ds_read_b64_tr_b16 v[218:219], v161 offset:34880
	ds_read_b64_tr_b16 v[220:221], v161 offset:35456
	ds_read_b64_tr_b16 v[222:223], v161 offset:34912
	ds_read_b64_tr_b16 v[224:225], v161 offset:35488
	s_waitcnt lgkmcnt(8)
	v_mfma_f32_16x16x32_bf16 v[198:201], v[230:233], v[234:237], v[198:201]
	v_mfma_f32_16x16x32_bf16 v[202:205], v[230:233], v[238:241], v[202:205]
	ds_read_b64_tr_b16 v[230:231], v161 offset:39424
	ds_read_b64_tr_b16 v[232:233], v161 offset:40000
	ds_read_b64_tr_b16 v[234:235], v161 offset:39456
	ds_read_b64_tr_b16 v[236:237], v161 offset:40032
	s_waitcnt lgkmcnt(8)
	v_mfma_f32_16x16x32_bf16 v[96:99], v[190:193], v[242:245], v[96:99]
	v_mfma_f32_16x16x32_bf16 v[100:103], v[190:193], v[246:249], v[100:103]
	ds_read_b64_tr_b16 v[242:243], v161 offset:39488
	ds_read_b64_tr_b16 v[244:245], v161 offset:40064
	ds_read_b64_tr_b16 v[246:247], v161 offset:39520
	ds_read_b64_tr_b16 v[248:249], v161 offset:40096
	v_cvt_pk_bf16_f32 v198, v198, v199
	v_cvt_pk_bf16_f32 v199, v200, v201
	v_add_u32_e32 v254, s48, v173
	v_mad_u64_u32 v[254:255], s[20:21], v254, s42, 0
	v_lshl_add_u64 v[254:255], v[254:255], 1, v[150:151]
	v_cvt_pk_bf16_f32 v202, v202, v203
	v_cvt_pk_bf16_f32 v203, v204, v205
	global_store_dwordx2 v[254:255], v[198:199], off
	v_add_u32_e32 v254, s48, v179
	v_mad_u64_u32 v[254:255], s[20:21], v254, s42, 0
	v_lshl_add_u64 v[254:255], v[254:255], 1, v[150:151]
	global_store_dwordx2 v[254:255], v[202:203], off
	s_waitcnt lgkmcnt(8)
	v_mfma_f32_16x16x32_bf16 v[104:107], v[190:193], v[218:221], v[104:107]
	v_mfma_f32_16x16x32_bf16 v[214:217], v[190:193], v[222:225], v[108:111]
	s_waitcnt lgkmcnt(4)
	v_mfma_f32_16x16x32_bf16 v[112:115], v[194:197], v[230:233], v[96:99]
	v_mfma_f32_16x16x32_bf16 v[108:111], v[194:197], v[234:237], v[100:103]
	s_waitcnt lgkmcnt(0)
	v_mfma_f32_16x16x32_bf16 v[104:107], v[194:197], v[242:245], v[104:107]
	v_mfma_f32_16x16x32_bf16 v[100:103], v[194:197], v[246:249], v[214:217]
	s_min_u32 s20, s44, 59
	s_waitcnt lgkmcnt(0)
	s_barrier
	s_waitcnt vmcnt(20)
	ds_write_b128 v168, v[72:75]
	s_waitcnt vmcnt(19)
	ds_write_b128 v168, v[80:83] offset:8704
	s_waitcnt vmcnt(18)
	ds_write_b128 v168, v[76:79] offset:17408
	s_waitcnt vmcnt(17)
	ds_write_b128 v168, v[84:87] offset:26112
	s_waitcnt vmcnt(16)
	ds_write_b128 v169, v[88:91] offset:34816
	v_add_u32_e32 v72, s34, v154
	s_add_i32 s34, s20, 4
	s_waitcnt vmcnt(15)
	s_cmp_lg_u32 s69, 0
	s_cbranch_scc1 .Lev_skip_b
	ds_write_b128 v72, v[92:95]
.Lev_skip_b:
	v_sub_u32_e64 v72, 59, s44 clamp
	s_and_b64 s[20:21], exec, s[38:39]
	v_readfirstlane_b32 s20, v72
	s_cselect_b32 s48, s34, s20
	v_add_u32_e32 v96, s61, v143
	s_lshl_b32 s34, s48, 13
	s_lshl_b32 s49, s48, 14
	ds_read_b128 v[186:189], v96
	s_add_u32 s20, s43, s49
	s_addc_u32 s21, s63, 0
	v_lshl_add_u64 v[76:77], s[20:21], 0, v[120:121]
	global_load_dwordx4 v[72:75], v120, s[20:21]
	v_add_co_u32_e64 v76, s[20:21], s60, v76
	s_waitcnt lgkmcnt(0)
	v_pk_mul_f32 v[118:119], v[118:119], v[188:189]
	v_addc_co_u32_e64 v77, s[20:21], 0, v77, s[20:21]
	v_pk_mul_f32 v[116:117], v[116:117], v[186:187]
	s_add_u32 s20, s64, s49
	v_pk_mul_f32 v[114:115], v[114:115], v[118:119]
	v_pk_mul_f32 v[112:113], v[112:113], v[116:117]
	s_addc_u32 s21, s65, 0
	v_add_u32_e32 v96, 0x1ea00, v185
	v_cvt_pk_bf16_f32 v186, v112, v113
	v_cvt_pk_bf16_f32 v187, v114, v115
	v_pk_mul_f32 v[110:111], v[110:111], v[118:119]
	v_pk_mul_f32 v[108:109], v[108:109], v[116:117]
	v_lshl_add_u64 v[84:85], s[20:21], 0, v[120:121]
	ds_read_b128 v[96:99], v96
	ds_write_b64 v182, v[186:187]
	v_cvt_pk_bf16_f32 v186, v108, v109
	v_cvt_pk_bf16_f32 v187, v110, v111
	v_pk_mul_f32 v[106:107], v[106:107], v[118:119]
	v_pk_mul_f32 v[104:105], v[104:105], v[116:117]
	v_pk_mul_f32 v[102:103], v[102:103], v[118:119]
	v_pk_mul_f32 v[100:101], v[100:101], v[116:117]
	global_load_dwordx4 v[80:83], v[76:77], off
	v_lshl_add_u64 v[88:89], v[146:147], 0, s[34:35]
	global_load_dwordx4 v[76:79], v120, s[20:21]
	v_add_co_u32_e64 v84, s[20:21], s60, v84
	s_lshl_b32 s34, s48, 10
	ds_write_b64 v182, v[186:187] offset:4352
	v_cvt_pk_bf16_f32 v186, v104, v105
	v_cvt_pk_bf16_f32 v187, v106, v107
	v_cvt_pk_bf16_f32 v116, v100, v101
	v_cvt_pk_bf16_f32 v117, v102, v103
	v_addc_co_u32_e64 v85, s[20:21], 0, v85, s[20:21]
	v_lshl_add_u64 v[92:93], v[148:149], 0, s[34:35]
	ds_write_b64 v182, v[186:187] offset:8704
	ds_write_b64 v182, v[116:117] offset:13056
	global_load_dwordx4 v[84:87], v[84:85], off
	v_add_u32_e32 v185, s31, v162
	global_load_dwordx4 v[88:91], v[88:89], off nt
	v_add_u32_e32 v194, s45, v159
	global_load_dwordx4 v[92:95], v[92:93], off
	s_waitcnt lgkmcnt(0)
	s_barrier
	ds_read_b128 v[218:221], v170 offset:17408
	ds_read_b128 v[222:225], v171
	ds_read_b128 v[226:229], v172
	ds_read_b128 v[230:233], v170 offset:17472
	ds_read_b128 v[234:237], v171 offset:64
	ds_read_b128 v[238:241], v172 offset:64
	ds_read_b128 v[242:245], v170 offset:17536
	ds_read_b128 v[246:249], v171 offset:128
	ds_read_b128 v[250:253], v172 offset:128
	s_add_i32 s34, s44, 1
	s_and_b64 s[20:21], exec, s[38:39]
	s_cselect_b32 s20, s34, s47
	s_lshl_b32 s34, s20, 6
	s_add_i32 s47, s47, -2
	v_lshl_add_u64 v[152:153], v[152:153], 0, s[36:37]
	s_waitcnt lgkmcnt(6)
	v_mfma_f32_16x16x32_bf16 v[190:193], v[218:221], v[222:225], 0
	v_mfma_f32_16x16x32_bf16 v[194:197], v[218:221], v[226:229], 0
	ds_read_b128 v[218:221], v170 offset:17600
	ds_read_b128 v[222:225], v171 offset:192
	ds_read_b128 v[226:229], v172 offset:192
	s_waitcnt lgkmcnt(6)
	v_mfma_f32_16x16x32_bf16 v[190:193], v[230:233], v[234:237], v[190:193]
	v_mfma_f32_16x16x32_bf16 v[194:197], v[230:233], v[238:241], v[194:197]
	ds_read_b64_tr_b16 v[230:231], v207
	ds_read_b64_tr_b16 v[232:233], v207 offset:576
	ds_read_b128 v[234:237], v210
	ds_read_b128 v[238:241], v211
	s_waitcnt lgkmcnt(7)
	v_mfma_f32_16x16x32_bf16 v[190:193], v[242:245], v[246:249], v[190:193]
	v_mfma_f32_16x16x32_bf16 v[194:197], v[242:245], v[250:253], v[194:197]
	ds_read_b64_tr_b16 v[242:243], v207 offset:4608
	ds_read_b64_tr_b16 v[244:245], v207 offset:5184
	ds_read_b128 v[246:249], v210 offset:64
	ds_read_b128 v[250:253], v211 offset:64
	s_waitcnt lgkmcnt(8)
	v_mfma_f32_16x16x32_bf16 v[190:193], v[218:221], v[222:225], v[190:193]
	v_mfma_f32_16x16x32_bf16 v[194:197], v[218:221], v[226:229], v[194:197]
	ds_read_b128 v[218:221], v183
	ds_read_b128 v[222:225], v171 offset:44032
	ds_read_b128 v[226:229], v172 offset:44032
	s_waitcnt lgkmcnt(7)
	v_mfma_f32_16x16x32_bf16 v[198:201], v[230:233], v[234:237], 0
	v_mfma_f32_16x16x32_bf16 v[202:205], v[230:233], v[238:241], 0
	ds_read_b128 v[230:233], v183 offset:64
	ds_read_b128 v[234:237], v171 offset:44096
	ds_read_b128 v[238:241], v172 offset:44096
	s_waitcnt lgkmcnt(6)
	v_mfma_f32_16x16x32_bf16 v[198:201], v[242:245], v[246:249], v[198:201]
	v_mfma_f32_16x16x32_bf16 v[202:205], v[242:245], v[250:253], v[202:205]
	ds_read_b128 v[242:245], v183 offset:128
	ds_read_b128 v[246:249], v171 offset:44160
	ds_read_b128 v[250:253], v172 offset:44160
	v_cndmask_b32_e32 v190, 0, v190, vcc
	v_cndmask_b32_e64 v191, 0, v191, s[6:7]
	v_cndmask_b32_e64 v192, 0, v192, s[8:9]
	v_cndmask_b32_e64 v193, 0, v193, s[10:11]
	v_cvt_pk_bf16_f32 v190, v190, v191
	v_cvt_pk_bf16_f32 v191, v192, v193
	v_cndmask_b32_e64 v194, 0, v194, s[12:13]
	v_cndmask_b32_e64 v195, 0, v195, s[14:15]
	v_cndmask_b32_e64 v196, 0, v196, s[16:17]
	v_cndmask_b32_e64 v197, 0, v197, s[18:19]
	v_cvt_pk_bf16_f32 v194, v194, v195
	v_cvt_pk_bf16_f32 v195, v196, v197
	ds_write_b64 v175, v[190:191]
	ds_write_b64 v177, v[194:195]
	s_waitcnt lgkmcnt(8)
	v_mfma_f32_16x16x32_bf16 v[198:201], v[218:221], v[222:225], v[198:201]
	v_mfma_f32_16x16x32_bf16 v[202:205], v[218:221], v[226:229], v[202:205]
	ds_read_b64_tr_b16 v[190:191], v178 offset:61440
	ds_read_b64_tr_b16 v[192:193], v178 offset:62528
	ds_read_b64_tr_b16 v[194:195], v181 offset:8704
	ds_read_b64_tr_b16 v[196:197], v181 offset:9792
	s_waitcnt lgkmcnt(9)
	v_mfma_f32_16x16x32_bf16 v[198:201], v[230:233], v[234:237], v[198:201]
	v_mfma_f32_16x16x32_bf16 v[202:205], v[230:233], v[238:241], v[202:205]
	ds_read_b128 v[230:233], v183 offset:192
	ds_read_b128 v[234:237], v171 offset:44224
	ds_read_b128 v[238:241], v172 offset:44224
	s_waitcnt lgkmcnt(9)
	v_mfma_f32_16x16x32_bf16 v[198:201], v[242:245], v[246:249], v[198:201]
	v_mfma_f32_16x16x32_bf16 v[202:205], v[242:245], v[250:253], v[202:205]
	ds_read_b64_tr_b16 v[242:243], v162
	ds_read_b64_tr_b16 v[244:245], v162 offset:576
	ds_read_b64_tr_b16 v[246:247], v162 offset:32
	ds_read_b64_tr_b16 v[248:249], v162 offset:608
	s_waitcnt lgkmcnt(7)
	ds_read_b64_tr_b16 v[218:219], v162 offset:64
	ds_read_b64_tr_b16 v[220:221], v162 offset:640
	ds_read_b64_tr_b16 v[222:223], v162 offset:96
	ds_read_b64_tr_b16 v[224:225], v162 offset:672
	s_waitcnt lgkmcnt(8)
	v_mfma_f32_16x16x32_bf16 v[198:201], v[230:233], v[234:237], v[198:201]
	v_mfma_f32_16x16x32_bf16 v[202:205], v[230:233], v[238:241], v[202:205]
	ds_read_b64_tr_b16 v[230:231], v162 offset:4608
	ds_read_b64_tr_b16 v[232:233], v162 offset:5184
	ds_read_b64_tr_b16 v[234:235], v162 offset:4640
	ds_read_b64_tr_b16 v[236:237], v162 offset:5216
	s_waitcnt lgkmcnt(8)
	v_mfma_f32_16x16x32_bf16 v[112:115], v[190:193], v[242:245], v[112:115]
	v_mfma_f32_16x16x32_bf16 v[108:111], v[190:193], v[246:249], v[108:111]
	ds_read_b64_tr_b16 v[242:243], v162 offset:4672
	ds_read_b64_tr_b16 v[244:245], v162 offset:5248
	ds_read_b64_tr_b16 v[246:247], v162 offset:4704
	ds_read_b64_tr_b16 v[248:249], v162 offset:5280
	v_cvt_pk_bf16_f32 v198, v198, v199
	v_cvt_pk_bf16_f32 v199, v200, v201
	v_add_u32_e32 v254, s34, v173
	v_mad_u64_u32 v[254:255], s[20:21], v254, s42, 0
	v_lshl_add_u64 v[254:255], v[254:255], 1, v[150:151]
	v_cvt_pk_bf16_f32 v202, v202, v203
	v_cvt_pk_bf16_f32 v203, v204, v205
	global_store_dwordx2 v[254:255], v[198:199], off
	v_add_u32_e32 v254, s34, v179
	v_mad_u64_u32 v[254:255], s[20:21], v254, s42, 0
	v_lshl_add_u64 v[254:255], v[254:255], 1, v[150:151]
	global_store_dwordx2 v[254:255], v[202:203], off
	s_waitcnt lgkmcnt(8)
	v_mfma_f32_16x16x32_bf16 v[214:217], v[190:193], v[218:221], v[104:107]
	v_mfma_f32_16x16x32_bf16 v[116:119], v[190:193], v[222:225], v[100:103]
	s_waitcnt lgkmcnt(4)
	v_mfma_f32_16x16x32_bf16 v[100:103], v[194:197], v[230:233], v[112:115]
	v_mfma_f32_16x16x32_bf16 v[104:107], v[194:197], v[234:237], v[108:111]
	s_waitcnt lgkmcnt(0)
	v_mfma_f32_16x16x32_bf16 v[108:111], v[194:197], v[242:245], v[214:217]
	v_mfma_f32_16x16x32_bf16 v[112:115], v[194:197], v[246:249], v[116:119]
	s_add_i32 s20, s44, 2
	s_cmp_lt_u32 s44, 62
	s_mov_b32 s44, s20
	s_waitcnt lgkmcnt(0)
	s_barrier
	s_cbranch_scc1 .LBB0_350
	s_add_i32 s30, s30, s28
	v_lshl_add_u64 v[140:141], v[140:141], 0, s[26:27]
	s_cmpk_lt_i32 s30, 0x100
	v_add_u32_e32 v165, s29, v165
	s_cbranch_scc1 .LBB0_344
